# P9 fp8 K-loop: the 16 LDS-DMA loads per iteration issued from the MFMA segments (same order; load-segment waits 8->6/2/6/2), on the v042 stack
# baseline (speedup 1.0000x reference)
.LBB0_1019:
	ds_read_b128 v[16:19], v183
	ds_read_b128 v[20:23], v183 offset:1024
	ds_read_b128 v[24:27], v183 offset:2048
	ds_read_b128 v[28:31], v183 offset:3072
	ds_read_b128 v[0:3], v184
	ds_read_b128 v[4:7], v184 offset:1024
	ds_read_b128 v[8:11], v184 offset:2048
	ds_read_b128 v[12:15], v184 offset:3072
	s_add_u32 s38, s36, 0xffe00080
	s_addc_u32 s39, s37, -1
	s_cmpk_eq_i32 s60, 0x7c
	s_cselect_b32 s41, s25, s39
	s_cselect_b32 s40, s56, s38
	s_cselect_b32 s39, s23, s59
	s_cselect_b32 s38, s57, s58
	v_lshl_add_u64 v[222:223], s[36:37], 0, v[164:165]
	ds_read_b128 v[172:175], v185
	ds_read_b128 v[176:179], v185 offset:1024
	ds_read_b128 v[188:191], v185 offset:2048
	ds_read_b128 v[192:195], v185 offset:3072
	ds_read_b128 v[196:199], v185 offset:4096
	ds_read_b128 v[200:203], v185 offset:5120
	ds_read_b128 v[204:207], v185 offset:6144
	ds_read_b128 v[208:211], v185 offset:7168
	v_lshl_add_u64 v[224:225], s[36:37], 0, v[166:167]
	s_waitcnt vmcnt(6)
	s_waitcnt lgkmcnt(0)
	s_barrier
	s_setprio 1
	s_waitcnt lgkmcnt(0)
	s_nop 1
	v_mfma_scale_f32_16x16x128_f8f6f4 v[156:159], v[16:23], v[172:179], v[156:159], v186, v186 op_sel_hi:[0,0,0]
	s_add_i32 m0, s31, 0xc000
	s_nop 0
	global_load_lds_dwordx4 v[222:223], off
	s_nop 1
	v_mfma_scale_f32_16x16x128_f8f6f4 v[152:155], v[24:31], v[172:179], v[152:155], v186, v186 op_sel_hi:[0,0,0]
	s_nop 1
	v_mfma_scale_f32_16x16x128_f8f6f4 v[148:151], v[16:23], v[188:195], v[148:151], v186, v186 op_sel_hi:[0,0,0]
	s_nop 1
	v_mfma_scale_f32_16x16x128_f8f6f4 v[144:147], v[24:31], v[188:195], v[144:147], v186, v186 op_sel_hi:[0,0,0]
	s_nop 1
	v_mfma_scale_f32_16x16x128_f8f6f4 v[140:143], v[16:23], v[196:203], v[140:143], v186, v186 op_sel_hi:[0,0,0]
	s_nop 1
	v_mfma_scale_f32_16x16x128_f8f6f4 v[124:127], v[24:31], v[196:203], v[124:127], v186, v186 op_sel_hi:[0,0,0]
	s_nop 1
	v_mfma_scale_f32_16x16x128_f8f6f4 v[116:119], v[16:23], v[204:211], v[116:119], v186, v186 op_sel_hi:[0,0,0]
	s_nop 1
	v_mfma_scale_f32_16x16x128_f8f6f4 v[108:111], v[24:31], v[204:211], v[108:111], v186, v186 op_sel_hi:[0,0,0]
	s_setprio 0
	s_setprio 1
	s_nop 1
	v_mfma_scale_f32_16x16x128_f8f6f4 v[136:139], v[0:7], v[172:179], v[136:139], v186, v186 op_sel_hi:[0,0,0]
	s_add_i32 m0, s31, 0xe000
	s_nop 0
	global_load_lds_dwordx4 v[224:225], off
	s_nop 1
	v_mfma_scale_f32_16x16x128_f8f6f4 v[132:135], v[8:15], v[172:179], v[132:135], v186, v186 op_sel_hi:[0,0,0]
	s_nop 1
	v_mfma_scale_f32_16x16x128_f8f6f4 v[128:131], v[0:7], v[188:195], v[128:131], v186, v186 op_sel_hi:[0,0,0]
	s_nop 1
	v_mfma_scale_f32_16x16x128_f8f6f4 v[120:123], v[8:15], v[188:195], v[120:123], v186, v186 op_sel_hi:[0,0,0]
	s_nop 1
	v_mfma_scale_f32_16x16x128_f8f6f4 v[112:115], v[0:7], v[196:203], v[112:115], v186, v186 op_sel_hi:[0,0,0]
	s_nop 1
	v_mfma_scale_f32_16x16x128_f8f6f4 v[104:107], v[8:15], v[196:203], v[104:107], v186, v186 op_sel_hi:[0,0,0]
	s_nop 1
	v_mfma_scale_f32_16x16x128_f8f6f4 v[100:103], v[0:7], v[204:211], v[100:103], v186, v186 op_sel_hi:[0,0,0]
	s_nop 1
	v_mfma_scale_f32_16x16x128_f8f6f4 v[96:99], v[8:15], v[204:211], v[96:99], v186, v186 op_sel_hi:[0,0,0]
	s_setprio 0
	s_barrier
	s_add_u32 s62, s38, 0x200000
	s_addc_u32 s63, s39, 0
	v_lshl_add_u64 v[172:173], s[38:39], 0, v[162:163]
	ds_read_b128 v[188:191], v185 offset:16384
	ds_read_b128 v[192:195], v185 offset:17408
	ds_read_b128 v[196:199], v185 offset:18432
	ds_read_b128 v[200:203], v185 offset:19456
	ds_read_b128 v[204:207], v185 offset:20480
	ds_read_b128 v[208:211], v185 offset:21504
	ds_read_b128 v[212:215], v185 offset:22528
	ds_read_b128 v[216:219], v185 offset:23552
	v_lshl_add_u64 v[174:175], s[38:39], 0, v[160:161]
	v_lshl_add_u64 v[226:227], s[62:63], 0, v[162:163]
	v_lshl_add_u64 v[228:229], s[62:63], 0, v[160:161]
	v_lshl_add_u64 v[176:177], s[40:41], 0, v[162:163]
	v_lshl_add_u64 v[178:179], s[40:41], 0, v[160:161]
	s_waitcnt vmcnt(2)
	s_waitcnt lgkmcnt(0)
	s_barrier
	s_setprio 1
	s_waitcnt lgkmcnt(0)
	s_nop 1
	v_mfma_scale_f32_16x16x128_f8f6f4 v[92:95], v[16:23], v[188:195], v[92:95], v186, v186 op_sel_hi:[0,0,0]
	s_add_i32 m0, s53, s42
	s_nop 0
	global_load_lds_dwordx4 v[172:173], off
	s_nop 1
	v_mfma_scale_f32_16x16x128_f8f6f4 v[88:91], v[24:31], v[188:195], v[88:91], v186, v186 op_sel_hi:[0,0,0]
	s_nop 1
	v_mfma_scale_f32_16x16x128_f8f6f4 v[84:87], v[16:23], v[196:203], v[84:87], v186, v186 op_sel_hi:[0,0,0]
	s_nop 1
	v_mfma_scale_f32_16x16x128_f8f6f4 v[80:83], v[24:31], v[196:203], v[80:83], v186, v186 op_sel_hi:[0,0,0]
	s_add_i32 s61, s53, s42
	s_add_i32 m0, s61, 0x2000
	s_nop 0
	global_load_lds_dwordx4 v[174:175], off
	s_nop 1
	v_mfma_scale_f32_16x16x128_f8f6f4 v[76:79], v[16:23], v[204:211], v[76:79], v186, v186 op_sel_hi:[0,0,0]
	s_nop 1
	v_mfma_scale_f32_16x16x128_f8f6f4 v[64:67], v[24:31], v[204:211], v[64:67], v186, v186 op_sel_hi:[0,0,0]
	s_add_i32 m0, s54, s42
	s_nop 0
	global_load_lds_dwordx4 v[226:227], off
	s_nop 1
	v_mfma_scale_f32_16x16x128_f8f6f4 v[52:55], v[16:23], v[212:219], v[52:55], v186, v186 op_sel_hi:[0,0,0]
	s_nop 1
	v_mfma_scale_f32_16x16x128_f8f6f4 v[44:47], v[24:31], v[212:219], v[44:47], v186, v186 op_sel_hi:[0,0,0]
	s_setprio 0
	s_setprio 1
	s_nop 1
	v_mfma_scale_f32_16x16x128_f8f6f4 v[72:75], v[0:7], v[188:195], v[72:75], v186, v186 op_sel_hi:[0,0,0]
	s_add_i32 s61, s54, s42
	s_add_i32 m0, s61, 0x2000
	s_nop 0
	global_load_lds_dwordx4 v[228:229], off
	s_nop 1
	v_mfma_scale_f32_16x16x128_f8f6f4 v[68:71], v[8:15], v[188:195], v[68:71], v186, v186 op_sel_hi:[0,0,0]
	s_nop 1
	v_mfma_scale_f32_16x16x128_f8f6f4 v[60:63], v[0:7], v[196:203], v[60:63], v186, v186 op_sel_hi:[0,0,0]
	s_nop 1
	v_mfma_scale_f32_16x16x128_f8f6f4 v[56:59], v[8:15], v[196:203], v[56:59], v186, v186 op_sel_hi:[0,0,0]
	s_mov_b32 m0, s31
	s_nop 0
	global_load_lds_dwordx4 v[176:177], off
	s_nop 1
	v_mfma_scale_f32_16x16x128_f8f6f4 v[48:51], v[0:7], v[204:211], v[48:51], v186, v186 op_sel_hi:[0,0,0]
	s_nop 1
	v_mfma_scale_f32_16x16x128_f8f6f4 v[40:43], v[8:15], v[204:211], v[40:43], v186, v186 op_sel_hi:[0,0,0]
	s_mov_b32 m0, s44
	s_nop 0
	global_load_lds_dwordx4 v[178:179], off
	s_nop 1
	v_mfma_scale_f32_16x16x128_f8f6f4 v[36:39], v[0:7], v[212:219], v[36:39], v186, v186 op_sel_hi:[0,0,0]
	s_nop 1
	v_mfma_scale_f32_16x16x128_f8f6f4 v[32:35], v[8:15], v[212:219], v[32:35], v186, v186 op_sel_hi:[0,0,0]
	s_setprio 0
	s_barrier
	s_add_i32 s61, 0, 0x18000
	s_add_i32 s62, 0, 0x1c000
	v_add_u32_e32 v12, s61, v181
	v_add_u32_e32 v28, s62, v181
	ds_read_b128 v[0:3], v12
	ds_read_b128 v[4:7], v12 offset:1024
	ds_read_b128 v[8:11], v12 offset:2048
	ds_read_b128 v[12:15], v12 offset:3072
	ds_read_b128 v[16:19], v28
	ds_read_b128 v[20:23], v28 offset:1024
	ds_read_b128 v[24:27], v28 offset:2048
	ds_read_b128 v[28:31], v28 offset:3072
	s_add_u32 s40, s40, 0x200000
	s_addc_u32 s41, s41, 0
	v_lshl_add_u64 v[222:223], s[40:41], 0, v[162:163]
	ds_read_b128 v[188:191], v185 offset:32768
	ds_read_b128 v[192:195], v185 offset:33792
	ds_read_b128 v[196:199], v185 offset:34816
	ds_read_b128 v[200:203], v185 offset:35840
	ds_read_b128 v[204:207], v185 offset:36864
	ds_read_b128 v[208:211], v185 offset:37888
	ds_read_b128 v[212:215], v185 offset:38912
	ds_read_b128 v[216:219], v185 offset:39936
	v_lshl_add_u64 v[224:225], s[40:41], 0, v[160:161]
	s_waitcnt vmcnt(6)
	s_waitcnt lgkmcnt(0)
	s_barrier
	s_setprio 1
	s_waitcnt lgkmcnt(0)
	s_nop 1
	v_mfma_scale_f32_16x16x128_f8f6f4 v[156:159], v[0:7], v[188:195], v[156:159], v186, v186 op_sel_hi:[0,0,0]
	s_mov_b32 m0, s45
	s_nop 0
	global_load_lds_dwordx4 v[222:223], off
	s_nop 1
	v_mfma_scale_f32_16x16x128_f8f6f4 v[152:155], v[8:15], v[188:195], v[152:155], v186, v186 op_sel_hi:[0,0,0]
	s_nop 1
	v_mfma_scale_f32_16x16x128_f8f6f4 v[148:151], v[0:7], v[196:203], v[148:151], v186, v186 op_sel_hi:[0,0,0]
	s_nop 1
	v_mfma_scale_f32_16x16x128_f8f6f4 v[144:147], v[8:15], v[196:203], v[144:147], v186, v186 op_sel_hi:[0,0,0]
	s_nop 1
	v_mfma_scale_f32_16x16x128_f8f6f4 v[140:143], v[0:7], v[204:211], v[140:143], v186, v186 op_sel_hi:[0,0,0]
	s_nop 1
	v_mfma_scale_f32_16x16x128_f8f6f4 v[124:127], v[8:15], v[204:211], v[124:127], v186, v186 op_sel_hi:[0,0,0]
	s_nop 1
	v_mfma_scale_f32_16x16x128_f8f6f4 v[116:119], v[0:7], v[212:219], v[116:119], v186, v186 op_sel_hi:[0,0,0]
	s_nop 1
	v_mfma_scale_f32_16x16x128_f8f6f4 v[108:111], v[8:15], v[212:219], v[108:111], v186, v186 op_sel_hi:[0,0,0]
	s_setprio 0
	s_setprio 1
	s_nop 1
	v_mfma_scale_f32_16x16x128_f8f6f4 v[136:139], v[16:23], v[188:195], v[136:139], v186, v186 op_sel_hi:[0,0,0]
	s_mov_b32 m0, s46
	s_nop 0
	global_load_lds_dwordx4 v[224:225], off
	s_nop 1
	v_mfma_scale_f32_16x16x128_f8f6f4 v[132:135], v[24:31], v[188:195], v[132:135], v186, v186 op_sel_hi:[0,0,0]
	s_nop 1
	v_mfma_scale_f32_16x16x128_f8f6f4 v[128:131], v[16:23], v[196:203], v[128:131], v186, v186 op_sel_hi:[0,0,0]
	s_nop 1
	v_mfma_scale_f32_16x16x128_f8f6f4 v[120:123], v[24:31], v[196:203], v[120:123], v186, v186 op_sel_hi:[0,0,0]
	s_nop 1
	v_mfma_scale_f32_16x16x128_f8f6f4 v[112:115], v[16:23], v[204:211], v[112:115], v186, v186 op_sel_hi:[0,0,0]
	s_nop 1
	v_mfma_scale_f32_16x16x128_f8f6f4 v[104:107], v[24:31], v[204:211], v[104:107], v186, v186 op_sel_hi:[0,0,0]
	s_nop 1
	v_mfma_scale_f32_16x16x128_f8f6f4 v[100:103], v[16:23], v[212:219], v[100:103], v186, v186 op_sel_hi:[0,0,0]
	s_nop 1
	v_mfma_scale_f32_16x16x128_f8f6f4 v[96:99], v[24:31], v[212:219], v[96:99], v186, v186 op_sel_hi:[0,0,0]
	s_setprio 0
	s_barrier
	s_add_u32 s38, s38, 0x200080
	s_addc_u32 s39, s39, 0
	v_lshl_add_u64 v[222:223], v[172:173], 0, s[6:7]
	ds_read_b128 v[188:191], v185 offset:49152
	ds_read_b128 v[192:195], v185 offset:50176
	ds_read_b128 v[196:199], v185 offset:51200
	ds_read_b128 v[200:203], v185 offset:52224
	ds_read_b128 v[204:207], v185 offset:53248
	ds_read_b128 v[208:211], v185 offset:54272
	ds_read_b128 v[212:215], v185 offset:55296
	ds_read_b128 v[216:219], v185 offset:56320
	v_lshl_add_u64 v[224:225], v[174:175], 0, s[6:7]
	v_lshl_add_u64 v[226:227], s[38:39], 0, v[162:163]
	v_lshl_add_u64 v[228:229], s[38:39], 0, v[160:161]
	v_lshl_add_u64 v[230:231], v[176:177], 0, s[6:7]
	v_lshl_add_u64 v[232:233], v[178:179], 0, s[6:7]
	s_waitcnt vmcnt(2)
	s_waitcnt lgkmcnt(0)
	s_barrier
	s_setprio 1
	s_waitcnt lgkmcnt(0)
	s_nop 1
	v_mfma_scale_f32_16x16x128_f8f6f4 v[92:95], v[0:7], v[188:195], v[92:95], v186, v186 op_sel_hi:[0,0,0]
	s_add_i32 m0, s61, s42
	s_nop 0
	global_load_lds_dwordx4 v[222:223], off
	s_nop 1
	v_mfma_scale_f32_16x16x128_f8f6f4 v[88:91], v[8:15], v[188:195], v[88:91], v186, v186 op_sel_hi:[0,0,0]
	s_nop 1
	v_mfma_scale_f32_16x16x128_f8f6f4 v[84:87], v[0:7], v[196:203], v[84:87], v186, v186 op_sel_hi:[0,0,0]
	s_nop 1
	v_mfma_scale_f32_16x16x128_f8f6f4 v[80:83], v[8:15], v[196:203], v[80:83], v186, v186 op_sel_hi:[0,0,0]
	s_add_i32 s40, s61, s42
	s_add_i32 m0, s40, 0x2000
	s_nop 0
	global_load_lds_dwordx4 v[224:225], off
	s_nop 1
	v_mfma_scale_f32_16x16x128_f8f6f4 v[76:79], v[0:7], v[204:211], v[76:79], v186, v186 op_sel_hi:[0,0,0]
	s_nop 1
	v_mfma_scale_f32_16x16x128_f8f6f4 v[64:67], v[8:15], v[204:211], v[64:67], v186, v186 op_sel_hi:[0,0,0]
	s_add_i32 m0, s62, s42
	s_nop 0
	global_load_lds_dwordx4 v[226:227], off
	s_nop 1
	v_mfma_scale_f32_16x16x128_f8f6f4 v[52:55], v[0:7], v[212:219], v[52:55], v186, v186 op_sel_hi:[0,0,0]
	s_nop 1
	v_mfma_scale_f32_16x16x128_f8f6f4 v[44:47], v[8:15], v[212:219], v[44:47], v186, v186 op_sel_hi:[0,0,0]
	s_setprio 0
	s_setprio 1
	s_nop 1
	v_mfma_scale_f32_16x16x128_f8f6f4 v[72:75], v[16:23], v[188:195], v[72:75], v186, v186 op_sel_hi:[0,0,0]
	s_add_i32 s40, s62, s42
	s_add_i32 m0, s40, 0x2000
	s_nop 0
	global_load_lds_dwordx4 v[228:229], off
	s_nop 1
	v_mfma_scale_f32_16x16x128_f8f6f4 v[68:71], v[24:31], v[188:195], v[68:71], v186, v186 op_sel_hi:[0,0,0]
	s_nop 1
	v_mfma_scale_f32_16x16x128_f8f6f4 v[60:63], v[16:23], v[196:203], v[60:63], v186, v186 op_sel_hi:[0,0,0]
	s_nop 1
	v_mfma_scale_f32_16x16x128_f8f6f4 v[56:59], v[24:31], v[196:203], v[56:59], v186, v186 op_sel_hi:[0,0,0]
	s_mov_b32 m0, s51
	s_nop 0
	global_load_lds_dwordx4 v[230:231], off
	s_nop 1
	v_mfma_scale_f32_16x16x128_f8f6f4 v[48:51], v[16:23], v[204:211], v[48:51], v186, v186 op_sel_hi:[0,0,0]
	s_nop 1
	v_mfma_scale_f32_16x16x128_f8f6f4 v[40:43], v[24:31], v[204:211], v[40:43], v186, v186 op_sel_hi:[0,0,0]
	s_mov_b32 m0, s52
	s_nop 0
	global_load_lds_dwordx4 v[232:233], off
	s_nop 1
	v_mfma_scale_f32_16x16x128_f8f6f4 v[36:39], v[16:23], v[212:219], v[36:39], v186, v186 op_sel_hi:[0,0,0]
	s_nop 1
	v_mfma_scale_f32_16x16x128_f8f6f4 v[32:35], v[24:31], v[212:219], v[32:35], v186, v186 op_sel_hi:[0,0,0]
	s_setprio 0
	s_barrier
	s_add_i32 s60, s60, 2
	s_add_u32 s36, s36, 0x100
	s_addc_u32 s37, s37, 0
	s_add_u32 s58, s58, 0x100
	s_addc_u32 s59, s59, 0
	s_cmpk_lt_u32 s60, 0x7e
	s_cbranch_scc1 .LBB0_1019
	s_nop 15
	s_nop 15
	s_andn2_b64 vcc, exec, s[12:13]
	s_cbranch_vccnz .LBB0_1022
	s_barrier
